# attention phase: one static s_setprio 1 for waves 4-7 (younger half) at phase entry, reset at exit (guide 7.4)
# baseline (speedup 1.0000x reference)
; __global__ void __launch_bounds__(512, 2) mega(Params P, int ph_lo, int ph_hi) {
;     ...
;         } else if (k == 4 && PHON(4)) {
;             for (int idx = c; idx < 256; idx += G) {
;                 const int b = idx >> 4, h = (idx >> 2) & 3, pr = idx & 3;
;                 attn_unit<true>(lds, qm, km, vm, obr, ssq_qn, ssq_qr, cl, b, h, 7 - pr);
.LBB0_340:
	s_andn2_b64 vcc, exec, s[0:1]
	s_cbranch_vccnz .LBB0_432
	s_cmpk_gt_i32 s62, 0xff
	s_cbranch_scc1 .LBB0_432
	s_add_u32 s0, s56, 0x8300000
	s_addc_u32 s1, s57, 0
	s_mov_b32 s22, s62
	s_mov_b32 s23, s62
	v_readfirstlane_b32 s8, v195
	s_cmpk_gt_u32 s8, 0xff
	s_cbranch_scc0 .Lattn_prio
	s_setprio 1

; __device__ __forceinline__ void store4(bf16_t* p, f32x4 v) { u32x2 w; w.x = pk2(v.x, v.y); w.y = pk2(v.z, v.w); *(u32x2*)p = w; }
; template <bool MLA>
; __device__ __forceinline__ void attn_unit(LAS unsigned char* lds, const bf16_t* Q, const bf16_t* Kp, const bf16_t* V, bf16_t* O, const float* ssq_qn, const float* ssq_qr, const float* cl, int b, int h, int qb) {
;     ...
;     const float lt = l_run + __shfl_xor(l_run, 32), inv = 1.f / lt;
;     bf16_t* op = O + qrow * 256 + h * 64 + 4 * hh;
; #pragma unroll
;     for (int g = 0; g < 4; ++g) {
;         store4(op + 8 * g, (f32x4){o0[4 * g] * inv, o0[4 * g + 1] * inv, o0[4 * g + 2] * inv, o0[4 * g + 3] * inv});
;         store4(op + 32 + 8 * g, (f32x4){o1[4 * g] * inv, o1[4 * g + 1] * inv, o1[4 * g + 2] * inv, o1[4 * g + 3] * inv});
;     }
.LBB0_343:
	ds_bpermute_b32 v36, v110, v108
	v_lshl_add_u64 v[34:35], s[0:1], 0, v[90:91]
	v_lshlrev_b32_e32 v0, 1, v103
	v_lshl_add_u64 v[34:35], v[34:35], 0, s[2:3]
	v_lshl_add_u64 v[34:35], v[34:35], 0, v[0:1]
	s_waitcnt lgkmcnt(0)
	v_add_f32_e32 v36, v108, v36
	v_div_scale_f32 v37, s[6:7], v36, v36, 1.0
	v_rcp_f32_e32 v38, v37
	v_div_scale_f32 v39, vcc, 1.0, v36, 1.0
	s_add_i32 s23, s23, s27
	v_fma_f32 v40, -v37, v38, 1.0
	v_fmac_f32_e32 v38, v40, v38
	v_mul_f32_e32 v40, v39, v38
	v_fma_f32 v41, -v37, v40, v39
	v_fmac_f32_e32 v40, v41, v38
	v_fma_f32 v37, -v37, v40, v39
	v_div_fmas_f32 v37, v37, v38, v40
	v_div_fixup_f32 v36, v37, v36, 1.0
	s_add_i32 s22, s22, s27
	s_cmpk_gt_i32 s23, 0xff
	v_and_b32_e32 v178, 32, v248
	v_mov_b32_e32 v179, 0
	v_lshrrev_b32_e32 v178, 2, v178
	v_lshl_add_u64 v[34:35], v[34:35], 0, v[178:179]
	v_pk_mul_f32 v[18:19], v[18:19], v[36:37] op_sel_hi:[1,0]
	v_pk_mul_f32 v[20:21], v[20:21], v[36:37] op_sel_hi:[1,0]
	v_pk_mul_f32 v[22:23], v[22:23], v[36:37] op_sel_hi:[1,0]
	v_pk_mul_f32 v[24:25], v[24:25], v[36:37] op_sel_hi:[1,0]
	v_cvt_pk_bf16_f32 v180, v18, v19
	v_cvt_pk_bf16_f32 v181, v20, v21
	v_cvt_pk_bf16_f32 v182, v22, v23
	v_cvt_pk_bf16_f32 v183, v24, v25
	s_nop 1
	v_permlane32_swap_b32_e32 v180, v182
	v_permlane32_swap_b32_e32 v181, v183
	global_store_dwordx4 v[34:35], v[180:183], off
	v_pk_mul_f32 v[26:27], v[26:27], v[36:37] op_sel_hi:[1,0]
	v_pk_mul_f32 v[28:29], v[28:29], v[36:37] op_sel_hi:[1,0]
	v_pk_mul_f32 v[30:31], v[30:31], v[36:37] op_sel_hi:[1,0]
	v_pk_mul_f32 v[32:33], v[32:33], v[36:37] op_sel_hi:[1,0]
	v_cvt_pk_bf16_f32 v184, v26, v27
	v_cvt_pk_bf16_f32 v185, v28, v29
	v_cvt_pk_bf16_f32 v186, v30, v31
	v_cvt_pk_bf16_f32 v187, v32, v33
	s_nop 1
	v_permlane32_swap_b32_e32 v184, v186
	v_permlane32_swap_b32_e32 v185, v187
	global_store_dwordx4 v[34:35], v[184:187], off offset:32
	v_pk_mul_f32 v[2:3], v[2:3], v[36:37] op_sel_hi:[1,0]
	v_pk_mul_f32 v[4:5], v[4:5], v[36:37] op_sel_hi:[1,0]
	v_pk_mul_f32 v[6:7], v[6:7], v[36:37] op_sel_hi:[1,0]
	v_pk_mul_f32 v[8:9], v[8:9], v[36:37] op_sel_hi:[1,0]
	v_cvt_pk_bf16_f32 v188, v2, v3
	v_cvt_pk_bf16_f32 v189, v4, v5
	v_cvt_pk_bf16_f32 v190, v6, v7
	v_cvt_pk_bf16_f32 v191, v8, v9
	s_nop 1
	v_permlane32_swap_b32_e32 v188, v190
	v_permlane32_swap_b32_e32 v189, v191
	global_store_dwordx4 v[34:35], v[188:191], off offset:64
	v_pk_mul_f32 v[10:11], v[10:11], v[36:37] op_sel_hi:[1,0]
	v_pk_mul_f32 v[12:13], v[12:13], v[36:37] op_sel_hi:[1,0]
	v_pk_mul_f32 v[14:15], v[14:15], v[36:37] op_sel_hi:[1,0]
	v_pk_mul_f32 v[16:17], v[16:17], v[36:37] op_sel_hi:[1,0]
	v_cvt_pk_bf16_f32 v232, v10, v11
	v_cvt_pk_bf16_f32 v233, v12, v13
	v_cvt_pk_bf16_f32 v234, v14, v15
	v_cvt_pk_bf16_f32 v235, v16, v17
	s_nop 1
	v_permlane32_swap_b32_e32 v232, v234
	v_permlane32_swap_b32_e32 v233, v235
	global_store_dwordx4 v[34:35], v[232:235], off offset:96
	s_setprio 0
	s_cbranch_scc1 .LBB0_432
